# reversed LRU unit order + nt loads on the expert-weight conversion stream, on top of previous
# speedup vs baseline: 1.0058x; 1.0058x over previous
; #define GAS __attribute__((address_space(1)))
; #define LAS __attribute__((address_space(3)))
; __device__ __forceinline__ void cvt_load(const CvtItem& c, int lane, f32x4 (&v)[8]) {
; #pragma unroll
;     for (int i = 0; i < 8; ++i) { const int kk = 4 * i + (lane >> 4); v[i] = *(const GAS f32x4*)(c.src + (size_t)kk * c.N + 4 * (lane & 15)); }
; }
; __device__ __forceinline__ void cvt_store(const CvtItem& c, const f32x4 (&v)[8], LAS float* scr, int lane) {
; #pragma unroll
;     for (int i = 0; i < 8; ++i) { const int kk = 4 * i + (lane >> 4); LAS float* p = scr + kk * 65 + 4 * (lane & 15); p[0] = v[i][0]; p[1] = v[i][1]; p[2] = v[i][2]; p[3] = v[i][3]; }
; template <class Map> __device__ __forceinline__ void cvt_run(const Args& a, LAS float* scr, int count, int wk, int nw, int lane, Map map) {
;     if (wk >= count) return;
;     CvtItem cur = cvt_decode(a, map(wk)); f32x4 v[8]; cvt_load(cur, lane, v);
;     for (int it = wk; it < count; it += nw) {
;         const int nx = it + nw; CvtItem nxt = cur; f32x4 vn[8];
;         if (nx < count) { nxt = cvt_decode(a, map(nx)); cvt_load(nxt, lane, vn); }
.LBB0_520:
	v_ashrrev_i32_e32 v68, 4, v125
	v_ashrrev_i32_e32 v17, 31, v68
	v_add_u32_e32 v70, 4, v68
	v_ashrrev_i32_e32 v67, 31, v70
	v_mul_lo_u32 v1, s36, v17
	v_mul_lo_u32 v4, s37, v68
	v_mad_u64_u32 v[2:3], s[38:39], s36, v68, 0
	v_lshlrev_b32_e32 v0, 2, v125
	v_add3_u32 v3, v3, v1, v4
	v_mul_lo_u32 v1, s36, v67
	v_mul_lo_u32 v8, s37, v70
	v_mad_u64_u32 v[6:7], s[38:39], s36, v70, 0
	v_and_b32_e32 v0, 60, v0
	v_add3_u32 v7, v7, v1, v8
	v_add_u32_e32 v72, 8, v68
	v_lshl_add_u64 v[2:3], v[2:3], 2, s[22:23]
	v_lshlrev_b32_e32 v4, 2, v0
	v_mov_b32_e32 v5, v16
	v_lshl_add_u64 v[6:7], v[6:7], 2, s[22:23]
	v_ashrrev_i32_e32 v69, 31, v72
	v_add_u32_e32 v76, 12, v68
	v_lshl_add_u64 v[2:3], v[2:3], 0, v[4:5]
	v_lshl_add_u64 v[6:7], v[6:7], 0, v[4:5]
	v_ashrrev_i32_e32 v71, 31, v76
	global_load_dwordx4 v[34:37], v[2:3], off nt
	global_load_dwordx4 v[38:41], v[6:7], off nt
	v_mul_lo_u32 v1, s36, v69
	v_mul_lo_u32 v6, s37, v72
	v_mad_u64_u32 v[2:3], s[38:39], s36, v72, 0
	v_add3_u32 v3, v3, v1, v6
	v_mul_lo_u32 v1, s36, v71
	v_mul_lo_u32 v8, s37, v76
	v_mad_u64_u32 v[6:7], s[38:39], s36, v76, 0
	v_add3_u32 v7, v7, v1, v8
	v_add_u32_e32 v78, 16, v68
	v_lshl_add_u64 v[2:3], v[2:3], 2, s[22:23]
	v_lshl_add_u64 v[6:7], v[6:7], 2, s[22:23]
	v_ashrrev_i32_e32 v73, 31, v78
	v_add_u32_e32 v80, 20, v68
	v_lshl_add_u64 v[2:3], v[2:3], 0, v[4:5]
	v_lshl_add_u64 v[6:7], v[6:7], 0, v[4:5]
	v_ashrrev_i32_e32 v75, 31, v80
	global_load_dwordx4 v[42:45], v[2:3], off nt
	global_load_dwordx4 v[46:49], v[6:7], off nt
	v_mul_lo_u32 v1, s36, v73
	v_mul_lo_u32 v6, s37, v78
	v_mad_u64_u32 v[2:3], s[38:39], s36, v78, 0
	v_add3_u32 v3, v3, v1, v6
	v_mul_lo_u32 v1, s36, v75
	v_mul_lo_u32 v8, s37, v80
	v_mad_u64_u32 v[6:7], s[38:39], s36, v80, 0
	v_add3_u32 v7, v7, v1, v8
	v_add_u32_e32 v82, 24, v68
	v_lshl_add_u64 v[2:3], v[2:3], 2, s[22:23]
	v_lshl_add_u64 v[6:7], v[6:7], 2, s[22:23]
	v_ashrrev_i32_e32 v77, 31, v82
	v_add_u32_e32 v84, 28, v68
	v_lshl_add_u64 v[2:3], v[2:3], 0, v[4:5]
	v_lshl_add_u64 v[6:7], v[6:7], 0, v[4:5]
	v_ashrrev_i32_e32 v79, 31, v84
	global_load_dwordx4 v[50:53], v[2:3], off nt
	global_load_dwordx4 v[54:57], v[6:7], off nt
	v_mul_lo_u32 v1, s36, v77
	v_mul_lo_u32 v6, s37, v82
	v_mad_u64_u32 v[2:3], s[38:39], s36, v82, 0
	v_add3_u32 v3, v3, v1, v6
	v_mul_lo_u32 v1, s36, v79
	v_mul_lo_u32 v8, s37, v84
	v_mad_u64_u32 v[6:7], s[36:37], s36, v84, 0
	v_lshl_add_u64 v[2:3], v[2:3], 2, s[22:23]
	v_add3_u32 v7, v7, v1, v8
	v_lshl_add_u64 v[2:3], v[2:3], 0, v[4:5]
	v_lshl_add_u64 v[6:7], v[6:7], 2, s[22:23]
	v_lshl_add_u64 v[6:7], v[6:7], 0, v[4:5]
	global_load_dwordx4 v[58:61], v[2:3], off nt
	global_load_dwordx4 v[62:65], v[6:7], off nt
	s_mul_i32 s4, s2, 0x2100
	s_add_i32 s4, s4, 0
	v_lshlrev_b32_e32 v2, 4, v125
	s_movk_i32 s21, 0x104
	v_and_b32_e32 v86, 16, v2
	v_mov_b32_e32 v5, s4
	v_ashrrev_i32_e32 v2, 1, v125
	v_mad_u32_u24 v6, v86, s21, v5
	v_ashrrev_i32_e32 v3, 31, v2
	v_lshl_add_u32 v81, v2, 2, v6
	v_lshlrev_b64 v[88:89], 10, v[2:3]
	v_lshlrev_b32_e32 v2, 3, v125
	v_and_b32_e32 v2, 24, v2
	v_mad_u32_u24 v5, v2, s21, v5
	v_lshlrev_b32_e32 v90, 1, v2
	v_ashrrev_i32_e32 v2, 2, v125
	v_and_b32_e32 v3, -4, v125
	v_add_u32_e32 v7, 64, v125
	v_add_u32_e32 v100, v5, v3
	v_ashrrev_i32_e32 v3, 31, v2
	v_lshlrev_b64 v[92:93], 11, v[2:3]
	v_ashrrev_i32_e32 v2, 2, v7
	v_and_b32_e32 v3, -4, v7
	v_add_u32_e32 v101, v5, v3
	v_ashrrev_i32_e32 v3, 31, v2
	v_lshlrev_b64 v[94:95], 11, v[2:3]
	v_add_u32_e32 v3, 0x80, v125
	v_ashrrev_i32_e32 v2, 2, v3
	v_and_b32_e32 v3, -4, v3
	v_add_u32_e32 v102, v5, v3
	v_ashrrev_i32_e32 v3, 31, v2
	v_lshlrev_b64 v[96:97], 11, v[2:3]
	v_add_u32_e32 v2, 0xc0, v125
	v_add_u32_e32 v1, s4, v4
	v_mul_lo_u32 v4, v68, s21
	v_ashrrev_i32_e32 v83, 1, v7
	v_ashrrev_i32_e32 v103, 2, v2
	v_and_b32_e32 v2, -4, v2
	s_lshl_b32 s4, s2, 5
	v_mov_b32_e32 v87, v16
	v_lshl_add_u32 v85, v83, 2, v6
	v_mov_b32_e32 v91, v16
	v_add_u32_e32 v104, v5, v2
	s_addk_i32 s4, 0x100
	v_lshlrev_b32_e32 v98, 2, v0
	v_add_u32_e32 v105, v1, v4
	s_mov_b32 s21, s2
	v_mov_b32_e32 v106, v74
	s_mov_b64 s[36:37], s[8:9]
	s_mov_b32 s25, s34
	s_branch .LBB0_522

; #define GAS __attribute__((address_space(1)))
; __device__ __forceinline__ void cvt_load(const CvtItem& c, int lane, f32x4 (&v)[8]) {
; #pragma unroll
;     for (int i = 0; i < 8; ++i) { const int kk = 4 * i + (lane >> 4); v[i] = *(const GAS f32x4*)(c.src + (size_t)kk * c.N + 4 * (lane & 15)); }
; }
; template <class Map> __device__ __forceinline__ void cvt_run(const Args& a, LAS float* scr, int count, int wk, int nw, int lane, Map map) {
;     ...
;     for (int it = wk; it < count; it += nw) {
;         const int nx = it + nw; CvtItem nxt = cur; f32x4 vn[8];
;         if (nx < count) { nxt = cvt_decode(a, map(nx)); cvt_load(nxt, lane, vn); }
.LBB0_535:
	v_mul_lo_u32 v2, s43, v68
	v_mul_lo_u32 v3, s42, v17
	v_mad_u64_u32 v[0:1], s[40:41], s42, v68, 0
	v_mul_lo_u32 v10, s43, v72
	v_mul_lo_u32 v11, s42, v69
	v_mad_u64_u32 v[8:9], s[40:41], s42, v72, 0
	v_mul_lo_u32 v20, s43, v78
	v_mul_lo_u32 v21, s42, v73
	v_mad_u64_u32 v[18:19], s[40:41], s42, v78, 0
	s_waitcnt vmcnt(13)
	v_mul_lo_u32 v28, s43, v82
	v_mul_lo_u32 v29, s42, v77
	v_mad_u64_u32 v[26:27], s[40:41], s42, v82, 0
	v_add3_u32 v1, v1, v3, v2
	v_mul_lo_u32 v4, s43, v70
	v_mul_lo_u32 v5, s42, v67
	v_mad_u64_u32 v[2:3], s[40:41], s42, v70, 0
	v_add3_u32 v9, v9, v11, v10
	v_mul_lo_u32 v12, s43, v76
	v_mul_lo_u32 v13, s42, v71
	v_mad_u64_u32 v[10:11], s[40:41], s42, v76, 0
	v_add3_u32 v19, v19, v21, v20
	v_mul_lo_u32 v22, s43, v80
	v_mul_lo_u32 v23, s42, v75
	v_mad_u64_u32 v[20:21], s[40:41], s42, v80, 0
	v_add3_u32 v27, v27, v29, v28
	v_mul_lo_u32 v30, s43, v84
	v_mul_lo_u32 v31, s42, v79
	v_mad_u64_u32 v[28:29], s[40:41], s42, v84, 0
	v_add3_u32 v3, v3, v5, v4
	v_add3_u32 v11, v11, v13, v12
	v_add3_u32 v21, v21, v23, v22
	v_add3_u32 v29, v29, v31, v30
	v_lshl_add_u64 v[0:1], v[0:1], 2, s[38:39]
	v_mov_b32_e32 v99, v16
	v_lshl_add_u64 v[2:3], v[2:3], 2, s[38:39]
	v_lshl_add_u64 v[8:9], v[8:9], 2, s[38:39]
	v_lshl_add_u64 v[10:11], v[10:11], 2, s[38:39]
	v_lshl_add_u64 v[18:19], v[18:19], 2, s[38:39]
	v_lshl_add_u64 v[20:21], v[20:21], 2, s[38:39]
	v_lshl_add_u64 v[26:27], v[26:27], 2, s[38:39]
	v_lshl_add_u64 v[28:29], v[28:29], 2, s[38:39]
	v_lshl_add_u64 v[0:1], v[0:1], 0, v[98:99]
	v_lshl_add_u64 v[2:3], v[2:3], 0, v[98:99]
	v_lshl_add_u64 v[8:9], v[8:9], 0, v[98:99]
	v_lshl_add_u64 v[10:11], v[10:11], 0, v[98:99]
	v_lshl_add_u64 v[18:19], v[18:19], 0, v[98:99]
	v_lshl_add_u64 v[20:21], v[20:21], 0, v[98:99]
	v_lshl_add_u64 v[26:27], v[26:27], 0, v[98:99]
	v_lshl_add_u64 v[28:29], v[28:29], 0, v[98:99]
	global_load_dwordx4 v[4:7], v[0:1], off nt
	s_nop 0
	global_load_dwordx4 v[0:3], v[2:3], off nt
	s_nop 0
	global_load_dwordx4 v[12:15], v[8:9], off nt
	s_nop 0
	global_load_dwordx4 v[8:11], v[10:11], off nt
	s_nop 0
	global_load_dwordx4 v[22:25], v[18:19], off nt
	s_nop 0
	global_load_dwordx4 v[18:21], v[20:21], off nt
	s_nop 0
	global_load_dwordx4 v[30:33], v[26:27], off nt
	s_nop 0
	global_load_dwordx4 v[26:29], v[28:29], off nt

; #define LAS __attribute__((address_space(3)))
; __device__ __forceinline__ unsigned pk2(float lo, float hi) { typedef __bf16 bf2_t __attribute__((ext_vector_type(2))); const f32x2 v = {lo, hi}; return __builtin_bit_cast(unsigned, __builtin_convertvector(v, bf2_t)); }
; __device__ __forceinline__ void unit(LAS unsigned char* lds, const Args& a, int l, int tk, int wave, int lane, int tid) {
;     const int b = tk >> 2, blk = tk & 3, fr = lane & 15, fq = lane >> 4;
;     const bf16* qkv = (const bf16*)(a.ws + WS_QKV); bf16* outg = (bf16*)(a.ws + WS_LRU);
;     LAS v4u* WF = (LAS v4u*)(lds + WF_OFF);
;     {
; #pragma unroll
;       for (int ff = 0; ff < 2; ++ff) { const int f = 2 * wave + ff, gate = f >> 3, nt = (f >> 1) & 3, s = f & 1;
;         const float* W = (gate ? a.in[I_WX] : a.in[I_WA]) + ((size_t)l * 4 + blk) * 64 * 64;
;         const int k0 = 32 * s + 8 * fq, oc = 16 * nt + fr; v4u pa;
;         pa.x = pk2(W[(k0 + 0) * 64 + oc], W[(k0 + 1) * 64 + oc]); pa.y = pk2(W[(k0 + 2) * 64 + oc], W[(k0 + 3) * 64 + oc]); pa.z = pk2(W[(k0 + 4) * 64 + oc], W[(k0 + 5) * 64 + oc]); pa.w = pk2(W[(k0 + 6) * 64 + oc], W[(k0 + 7) * 64 + oc]);
;         WF[f * 64 + lane] = pa; } }
;     float ba[4], bx[4], csp[4], carry[4];
; #pragma unroll
;     for (int nt = 0; nt < 4; ++nt) { const int ch = l * LW + 64 * blk + 16 * nt + fr; ba[nt] = a.in[I_BA][ch]; bx[nt] = a.in[I_BX][ch]; csp[nt] = 8.0f * log1pf(expf(-a.in[I_LAM][ch])); carry[nt] = 0.f; }
;     const int c8 = tid & 7, chb = 64 * blk + 8 * c8;
;     LAS unsigned char* XC = lds + XC_OFF; LAS float* XCF = (LAS float*)(lds + XCF_OFF); LAS bf16* XG = (LAS bf16*)(lds + XG_OFF); LAS bf16* OUT = (LAS bf16*)(lds + OUT_OFF); LAS float* AGG = (LAS float*)(lds + AGG_OFF);
;     LAS float* CWL = (LAS float*)(lds + CWL_OFF);
;     if (tid < 320) { const int j = tid >> 6, ch = tid & 63; CWL[tid] = j < 4 ? a.in[I_CONVW][((size_t)l * 4 + j) * LW + 64 * blk + ch] : a.in[I_CONVB][l * LW + 64 * blk + ch]; }
.LBB0_543:
	s_andn2_b64 vcc, exec, s[8:9]
	s_cbranch_vccnz .LBB0_236
	s_sub_i32 s62, 0x7f, s62
	s_lshl_b32 s4, s2, 4
	s_lshl_b32 s9, s2, 11
	s_and_b32 s3, s62, 3
	v_ashrrev_i32_e32 v72, 4, v125
	s_and_b32 s8, s4, 48
	s_add_i32 s9, s9, 0
	v_readlane_b32 s36, v250, 0
	v_and_b32_e32 v17, 15, v125
	s_cmp_lt_u32 s2, 4
	v_lshlrev_b32_e32 v0, 9, v72
	v_readlane_b32 s38, v250, 2
	v_or3_b32 v6, s8, v0, v17
	v_lshl_add_u32 v0, v125, 4, s9
	v_readlane_b32 s39, v250, 3
	s_cselect_b32 s9, s94, s38
	v_readlane_b32 s22, v255, 6
	s_cselect_b32 s8, s95, s39
	v_readlane_b32 s23, v255, 7
	s_add_u32 s9, s9, s22
	s_addc_u32 s21, s8, s23
	s_lshl_b32 s8, s3, 14
	s_add_u32 s8, s9, s8
	s_addc_u32 s9, s21, 0
	v_ashrrev_i32_e32 v7, 31, v6
	v_lshl_add_u64 v[8:9], v[6:7], 2, s[8:9]
	v_add_u32_e32 v5, 0x16800, v0
	global_load_dword v0, v[8:9], off
	global_load_dword v1, v[8:9], off offset:256
	s_lshl_b32 s3, s3, 6
	v_readlane_b32 s37, v250, 1
	v_readlane_b32 s40, v250, 4
	v_readlane_b32 s41, v250, 5
	v_readlane_b32 s42, v250, 6
	v_readlane_b32 s43, v250, 7
	v_add_u32_e32 v4, s74, v125
	v_readlane_b32 s44, v250, 8
	v_readlane_b32 s45, v250, 9
	v_readlane_b32 s46, v250, 10
	v_readlane_b32 s47, v250, 11
	v_readlane_b32 s48, v250, 12
	v_readlane_b32 s49, v250, 13
	v_readlane_b32 s50, v250, 14
	v_readlane_b32 s51, v250, 15
	s_waitcnt vmcnt(0)
	v_cvt_pk_bf16_f32 v0, v0, v1
	global_load_dword v1, v[8:9], off offset:512
	global_load_dword v2, v[8:9], off offset:768
	s_waitcnt vmcnt(0)
	v_cvt_pk_bf16_f32 v1, v1, v2
	global_load_dword v2, v[8:9], off offset:1024
	global_load_dword v3, v[8:9], off offset:1280
	s_waitcnt vmcnt(0)
	v_cvt_pk_bf16_f32 v2, v2, v3
	global_load_dword v3, v[8:9], off offset:1536
	global_load_dword v7, v[8:9], off offset:1792
	s_waitcnt vmcnt(0)
	v_cvt_pk_bf16_f32 v3, v3, v7
	ds_write_b128 v5, v[0:3]
	v_add_u32_e32 v0, 0x800, v6
	v_ashrrev_i32_e32 v1, 31, v0
	v_lshl_add_u64 v[6:7], v[0:1], 2, s[8:9]
	global_load_dword v0, v[6:7], off
	global_load_dword v1, v[6:7], off offset:256
	v_readlane_b32 s8, v255, 8
	s_or_b32 s21, s3, s8
	s_movk_i32 s8, 0x140
	v_cmp_gt_i32_e32 vcc, s8, v4
	s_waitcnt vmcnt(0)
	v_cvt_pk_bf16_f32 v0, v0, v1
	global_load_dword v1, v[6:7], off offset:512
	global_load_dword v2, v[6:7], off offset:768
	s_waitcnt vmcnt(0)
	v_cvt_pk_bf16_f32 v1, v1, v2
	global_load_dword v2, v[6:7], off offset:1024
	global_load_dword v3, v[6:7], off offset:1280
	s_waitcnt vmcnt(0)
	v_cvt_pk_bf16_f32 v2, v2, v3
	global_load_dword v3, v[6:7], off offset:1536
	s_nop 0
	global_load_dword v6, v[6:7], off offset:1792
	s_waitcnt vmcnt(0)
	v_cvt_pk_bf16_f32 v3, v3, v6
	ds_write_b128 v5, v[0:3] offset:1024
	v_or_b32_e32 v0, s21, v17
	v_mov_b32_e32 v1, v16
	v_lshlrev_b64 v[0:1], 2, v[0:1]
	v_lshl_add_u64 v[2:3], s[36:37], 0, v[0:1]
	v_lshl_add_u64 v[6:7], s[40:41], 0, v[0:1]
	v_lshl_add_u64 v[0:1], s[42:43], 0, v[0:1]
	global_load_dword v67, v[2:3], off
	global_load_dword v106, v[6:7], off
	global_load_dword v79, v[0:1], off
	global_load_dword v107, v[2:3], off offset:64
	global_load_dword v108, v[6:7], off offset:64
	global_load_dword v78, v[0:1], off offset:64
	global_load_dword v109, v[2:3], off offset:128
	global_load_dword v110, v[6:7], off offset:128
	global_load_dword v77, v[0:1], off offset:128
	global_load_dword v111, v[2:3], off offset:192
	global_load_dword v112, v[6:7], off offset:192
	global_load_dword v76, v[0:1], off offset:192
	s_and_saveexec_b64 s[8:9], vcc
	s_mov_b64 s[36:37], 0x1200
	s_cbranch_execz .LBB0_550
	v_ashrrev_i32_e32 v2, 6, v4
	v_and_b32_e32 v5, 63, v125
	v_cmp_lt_i32_e32 vcc, 3, v2
	s_and_saveexec_b64 s[22:23], vcc
	s_xor_b64 s[22:23], exec, s[22:23]
	v_or_b32_e32 v0, s21, v5
	v_mov_b32_e32 v1, v16
	v_lshl_add_u64 v[0:1], v[0:1], 2, s[92:93]
	s_andn2_saveexec_b64 s[22:23], s[22:23]
	s_cbranch_execz .LBB0_549
	v_ashrrev_i32_e32 v3, 31, v2
	v_readlane_b32 s34, v255, 9
	v_lshlrev_b64 v[0:1], 10, v[2:3]
	v_readlane_b32 s35, v255, 10
	v_lshlrev_b32_e32 v2, 2, v5
	v_mov_b32_e32 v3, v16
	v_lshl_add_u64 v[0:1], s[34:35], 0, v[0:1]
	v_readlane_b32 s34, v254, 39
	v_readlane_b32 s35, v254, 40
	s_lshl_b32 s34, s3, 2
	s_mov_b32 s21, s35
	v_writelane_b32 v254, s20, 39
	v_lshl_add_u64 v[0:1], v[0:1], 0, s[34:35]
	v_lshl_add_u64 v[0:1], v[0:1], 0, v[2:3]
	v_writelane_b32 v254, s21, 40
